# rs-stat issue/commit moved to trailing wave half (off the critical path)
# speedup vs baseline: 1.0203x; 1.0103x over previous
;     __device__ __forceinline__ void issue(const Unit& u, Pre& p) const {
;         int t = threadIdx.x; asm volatile("" : "+v"(t));
;         if (t < 256) { gp_t g = (gp_t)(ssq + (size_t)(u.pm * BM + t) * 16); p.a = g[0]; p.b = g[1]; p.c = g[2]; p.d = g[3]; }
;     }
.LBB0_124:
	s_andn2_b64 vcc, exec, s[2:3]
	s_cbranch_vccnz .LBB0_128
	v_add_u32_e32 v158, 0xffffff00, v204
	s_nop 0
	v_cmp_gt_u32_e32 vcc, s68, v158
	s_and_saveexec_b64 s[2:3], vcc
	s_cbranch_execz .LBB0_127
	s_nop 0
	v_lshl_add_u32 v2, s12, 8, v158
	v_ashrrev_i32_e32 v3, 31, v2
	v_lshlrev_b64 v[2:3], 6, v[2:3]
	v_lshl_add_u64 v[14:15], s[4:5], 0, v[2:3]
	global_load_dwordx4 v[2:5], v[14:15], off offset:48
	global_load_dwordx4 v[6:9], v[14:15], off offset:32
	global_load_dwordx4 v[10:13], v[14:15], off offset:16
	s_nop 0
	global_load_dwordx4 v[14:17], v[14:15], off

; __device__ __forceinline__ unsigned cvt_pk_bf16(float lo, float hi) { unsigned r; asm volatile("v_cvt_pk_bf16_f32 %0, %1, %2" : "=v"(r) : "v"(lo), "v"(hi)); return r; }
; __device__ __forceinline__ float silu_f(float g) { return g * __builtin_amdgcn_rcpf(1.0f + __expf(-g)); }
;     __device__ __forceinline__ void operator()(const f32x4 (&acc)[2][2][4][2], const Unit& u, int ui, int wr, int wc, int fr, int fq) const {
;         const int row0 = u.pm * BM + wr * 64 + fr, col0 = u.pn * HALF + wc * 32 + 8 * fq;
; #pragma unroll
;         for (int ai = 0; ai < 2; ++ai)
; #pragma unroll
;             for (int m = 0; m < 4; ++m) {
;                 const int row = row0 + ai * HALF + m * 16;
;                 const float s = rsb[(ui & 1) * 256 + ai * HALF + wr * 64 + m * 16 + fr];
;                 f32x4 g0 = acc[ai][0][m][0] * s, g1 = acc[ai][0][m][1] * s, u0 = acc[ai][1][m][0] * s, u1 = acc[ai][1][m][1] * s;
;                 u32x4 w;
;                 w.x = cvt_pk_bf16(silu_f(g0[0]) * u0[0], silu_f(g0[1]) * u0[1]); w.y = cvt_pk_bf16(silu_f(g0[2]) * u0[2], silu_f(g0[3]) * u0[3]);
;                 w.z = cvt_pk_bf16(silu_f(g1[0]) * u1[0], silu_f(g1[1]) * u1[1]); w.w = cvt_pk_bf16(silu_f(g1[2]) * u1[2], silu_f(g1[3]) * u1[3]);
;                 *(u32x4*)(H + (size_t)row * ldh + col0) = w;
;             }
;     }
.LBB0_128:
	s_lshl_b32 s2, s61, 10
	s_and_b32 s2, s2, 0x400
	v_add_u32_e32 v165, s2, v162
	ds_read_b32 v176, v165
	ds_read_b32 v178, v165 offset:64
	ds_read_b32 v180, v165 offset:128
	ds_read_b32 v182, v165 offset:192
	ds_read_b32 v184, v165 offset:512
	ds_read_b32 v186, v165 offset:576
	ds_read_b32 v188, v165 offset:640
	ds_read_b32 v190, v165 offset:704
	v_lshl_or_b32 v158, s45, 7, v161
	v_lshl_add_u32 v164, s44, 8, v1
	v_ashrrev_i32_e32 v159, 31, v158
	s_mov_b32 s98, 0x16000
	s_mov_b32 s99, 0
	s_mov_b32 s100, 0x6e000
	s_mov_b32 s101, 0
	v_mov_b32_e32 v172, 0xbfb8aa3b
	v_mov_b32_e32 v174, 1.0
	v_mov_b64_e32 v[166:167], s[8:9]
	v_mad_i64_i32 v[192:193], s[2:3], v164, s71, v[166:167]
	v_lshlrev_b64 v[166:167], 1, v[158:159]
	v_lshl_add_u64 v[192:193], v[192:193], 0, v[166:167]
	s_waitcnt lgkmcnt(0)
	v_pk_mul_f32 v[142:143], v[142:143], v[176:177] op_sel_hi:[1,0]
	v_pk_mul_f32 v[144:145], v[144:145], v[176:177] op_sel_hi:[1,0]
	v_pk_mul_f32 v[138:139], v[138:139], v[176:177] op_sel_hi:[1,0]
	v_pk_mul_f32 v[140:141], v[140:141], v[176:177] op_sel_hi:[1,0]
	v_pk_mul_f32 v[134:135], v[134:135], v[176:177] op_sel_hi:[1,0]
	v_pk_mul_f32 v[136:137], v[136:137], v[176:177] op_sel_hi:[1,0]
	v_pk_mul_f32 v[130:131], v[130:131], v[176:177] op_sel_hi:[1,0]
	v_pk_mul_f32 v[132:133], v[132:133], v[176:177] op_sel_hi:[1,0]
	v_pk_mul_f32 v[168:169], v[142:143], v[172:173] op_sel_hi:[1,0]
	v_pk_mul_f32 v[170:171], v[144:145], v[172:173] op_sel_hi:[1,0]
	v_exp_f32_e32 v168, v168
	v_exp_f32_e32 v169, v169
	v_exp_f32_e32 v170, v170
	v_exp_f32_e32 v171, v171
	v_pk_add_f32 v[168:169], v[168:169], v[174:175] op_sel_hi:[1,0]
	v_pk_add_f32 v[170:171], v[170:171], v[174:175] op_sel_hi:[1,0]
	v_rcp_f32_e32 v168, v168
	v_rcp_f32_e32 v169, v169
	v_rcp_f32_e32 v170, v170
	v_rcp_f32_e32 v171, v171
	v_pk_mul_f32 v[142:143], v[142:143], v[168:169]
	v_pk_mul_f32 v[144:145], v[144:145], v[170:171]
	v_pk_mul_f32 v[134:135], v[134:135], v[142:143]
	v_pk_mul_f32 v[136:137], v[136:137], v[144:145]
	v_cvt_pk_bf16_f32 v134, v134, v135
	v_cvt_pk_bf16_f32 v135, v136, v137
	v_pk_mul_f32 v[168:169], v[138:139], v[172:173] op_sel_hi:[1,0]
	v_pk_mul_f32 v[170:171], v[140:141], v[172:173] op_sel_hi:[1,0]
	v_exp_f32_e32 v168, v168
	v_exp_f32_e32 v169, v169
	v_exp_f32_e32 v170, v170
	v_exp_f32_e32 v171, v171
	v_pk_add_f32 v[168:169], v[168:169], v[174:175] op_sel_hi:[1,0]
	v_pk_add_f32 v[170:171], v[170:171], v[174:175] op_sel_hi:[1,0]
	v_rcp_f32_e32 v168, v168
	v_rcp_f32_e32 v169, v169
	v_rcp_f32_e32 v170, v170
	v_rcp_f32_e32 v171, v171
	v_pk_mul_f32 v[138:139], v[138:139], v[168:169]
	v_pk_mul_f32 v[140:141], v[140:141], v[170:171]
	v_pk_mul_f32 v[130:131], v[130:131], v[138:139]
	v_pk_mul_f32 v[132:133], v[132:133], v[140:141]
	v_cvt_pk_bf16_f32 v136, v130, v131
	v_cvt_pk_bf16_f32 v137, v132, v133
	global_store_dwordx4 v[192:193], v[134:137], off
	v_lshl_add_u64 v[192:193], v[192:193], 0, s[98:99]
	v_pk_mul_f32 v[126:127], v[126:127], v[178:179] op_sel_hi:[1,0]
	v_pk_mul_f32 v[128:129], v[128:129], v[178:179] op_sel_hi:[1,0]
	v_pk_mul_f32 v[122:123], v[122:123], v[178:179] op_sel_hi:[1,0]
	v_pk_mul_f32 v[124:125], v[124:125], v[178:179] op_sel_hi:[1,0]
	v_pk_mul_f32 v[118:119], v[118:119], v[178:179] op_sel_hi:[1,0]
	v_pk_mul_f32 v[120:121], v[120:121], v[178:179] op_sel_hi:[1,0]
	v_pk_mul_f32 v[114:115], v[114:115], v[178:179] op_sel_hi:[1,0]
	v_pk_mul_f32 v[116:117], v[116:117], v[178:179] op_sel_hi:[1,0]
	v_pk_mul_f32 v[168:169], v[126:127], v[172:173] op_sel_hi:[1,0]
	v_pk_mul_f32 v[170:171], v[128:129], v[172:173] op_sel_hi:[1,0]
	v_exp_f32_e32 v168, v168
	v_exp_f32_e32 v169, v169
	v_exp_f32_e32 v170, v170
	v_exp_f32_e32 v171, v171
	v_pk_add_f32 v[168:169], v[168:169], v[174:175] op_sel_hi:[1,0]
	v_pk_add_f32 v[170:171], v[170:171], v[174:175] op_sel_hi:[1,0]
	v_rcp_f32_e32 v168, v168
	v_rcp_f32_e32 v169, v169
	v_rcp_f32_e32 v170, v170
	v_rcp_f32_e32 v171, v171
	v_pk_mul_f32 v[126:127], v[126:127], v[168:169]
	v_pk_mul_f32 v[128:129], v[128:129], v[170:171]
	v_pk_mul_f32 v[118:119], v[118:119], v[126:127]
	v_pk_mul_f32 v[120:121], v[120:121], v[128:129]
	v_cvt_pk_bf16_f32 v118, v118, v119
	v_cvt_pk_bf16_f32 v119, v120, v121
	v_pk_mul_f32 v[168:169], v[122:123], v[172:173] op_sel_hi:[1,0]
	v_pk_mul_f32 v[170:171], v[124:125], v[172:173] op_sel_hi:[1,0]
	v_exp_f32_e32 v168, v168
	v_exp_f32_e32 v169, v169
	v_exp_f32_e32 v170, v170
	v_exp_f32_e32 v171, v171
	v_pk_add_f32 v[168:169], v[168:169], v[174:175] op_sel_hi:[1,0]
	v_pk_add_f32 v[170:171], v[170:171], v[174:175] op_sel_hi:[1,0]
	v_rcp_f32_e32 v168, v168
	v_rcp_f32_e32 v169, v169
	v_rcp_f32_e32 v170, v170
	v_rcp_f32_e32 v171, v171
	v_pk_mul_f32 v[122:123], v[122:123], v[168:169]
	v_pk_mul_f32 v[124:125], v[124:125], v[170:171]
	v_pk_mul_f32 v[114:115], v[114:115], v[122:123]
	v_pk_mul_f32 v[116:117], v[116:117], v[124:125]
	v_cvt_pk_bf16_f32 v120, v114, v115
	v_cvt_pk_bf16_f32 v121, v116, v117
	global_store_dwordx4 v[192:193], v[118:121], off
	v_lshl_add_u64 v[192:193], v[192:193], 0, s[98:99]
	v_pk_mul_f32 v[110:111], v[110:111], v[180:181] op_sel_hi:[1,0]
	v_pk_mul_f32 v[112:113], v[112:113], v[180:181] op_sel_hi:[1,0]
	v_pk_mul_f32 v[106:107], v[106:107], v[180:181] op_sel_hi:[1,0]
	v_pk_mul_f32 v[108:109], v[108:109], v[180:181] op_sel_hi:[1,0]
	v_pk_mul_f32 v[102:103], v[102:103], v[180:181] op_sel_hi:[1,0]
	v_pk_mul_f32 v[104:105], v[104:105], v[180:181] op_sel_hi:[1,0]
	v_pk_mul_f32 v[98:99], v[98:99], v[180:181] op_sel_hi:[1,0]
	v_pk_mul_f32 v[100:101], v[100:101], v[180:181] op_sel_hi:[1,0]
	v_pk_mul_f32 v[168:169], v[110:111], v[172:173] op_sel_hi:[1,0]
	v_pk_mul_f32 v[170:171], v[112:113], v[172:173] op_sel_hi:[1,0]
; __device__ __forceinline__ unsigned cvt_pk_bf16(float lo, float hi) { unsigned r; asm volatile("v_cvt_pk_bf16_f32 %0, %1, %2" : "=v"(r) : "v"(lo), "v"(hi)); return r; }
; __device__ __forceinline__ float silu_f(float g) { return g * __builtin_amdgcn_rcpf(1.0f + __expf(-g)); }
;     __device__ __forceinline__ void operator()(const f32x4 (&acc)[2][2][4][2], const Unit& u, int ui, int wr, int wc, int fr, int fq) const {
;         const int row0 = u.pm * BM + wr * 64 + fr, col0 = u.pn * HALF + wc * 32 + 8 * fq;
; #pragma unroll
;         for (int ai = 0; ai < 2; ++ai)
; #pragma unroll
;             for (int m = 0; m < 4; ++m) {
;                 const int row = row0 + ai * HALF + m * 16;
;                 const float s = rsb[(ui & 1) * 256 + ai * HALF + wr * 64 + m * 16 + fr];
;                 f32x4 g0 = acc[ai][0][m][0] * s, g1 = acc[ai][0][m][1] * s, u0 = acc[ai][1][m][0] * s, u1 = acc[ai][1][m][1] * s;
;                 u32x4 w;
;                 w.x = cvt_pk_bf16(silu_f(g0[0]) * u0[0], silu_f(g0[1]) * u0[1]); w.y = cvt_pk_bf16(silu_f(g0[2]) * u0[2], silu_f(g0[3]) * u0[3]);
;                 w.z = cvt_pk_bf16(silu_f(g1[0]) * u1[0], silu_f(g1[1]) * u1[1]); w.w = cvt_pk_bf16(silu_f(g1[2]) * u1[2], silu_f(g1[3]) * u1[3]);
;                 *(u32x4*)(H + (size_t)row * ldh + col0) = w;
;             }
;     }
	v_exp_f32_e32 v168, v168
	v_exp_f32_e32 v169, v169
	v_exp_f32_e32 v170, v170
	v_exp_f32_e32 v171, v171
	v_pk_add_f32 v[168:169], v[168:169], v[174:175] op_sel_hi:[1,0]
	v_pk_add_f32 v[170:171], v[170:171], v[174:175] op_sel_hi:[1,0]
	v_rcp_f32_e32 v168, v168
	v_rcp_f32_e32 v169, v169
	v_rcp_f32_e32 v170, v170
	v_rcp_f32_e32 v171, v171
	v_pk_mul_f32 v[110:111], v[110:111], v[168:169]
	v_pk_mul_f32 v[112:113], v[112:113], v[170:171]
	v_pk_mul_f32 v[102:103], v[102:103], v[110:111]
	v_pk_mul_f32 v[104:105], v[104:105], v[112:113]
	v_cvt_pk_bf16_f32 v102, v102, v103
	v_cvt_pk_bf16_f32 v103, v104, v105
	v_pk_mul_f32 v[168:169], v[106:107], v[172:173] op_sel_hi:[1,0]
	v_pk_mul_f32 v[170:171], v[108:109], v[172:173] op_sel_hi:[1,0]
	v_exp_f32_e32 v168, v168
	v_exp_f32_e32 v169, v169
	v_exp_f32_e32 v170, v170
	v_exp_f32_e32 v171, v171
	v_pk_add_f32 v[168:169], v[168:169], v[174:175] op_sel_hi:[1,0]
	v_pk_add_f32 v[170:171], v[170:171], v[174:175] op_sel_hi:[1,0]
	v_rcp_f32_e32 v168, v168
	v_rcp_f32_e32 v169, v169
	v_rcp_f32_e32 v170, v170
	v_rcp_f32_e32 v171, v171
	v_pk_mul_f32 v[106:107], v[106:107], v[168:169]
	v_pk_mul_f32 v[108:109], v[108:109], v[170:171]
	v_pk_mul_f32 v[98:99], v[98:99], v[106:107]
	v_pk_mul_f32 v[100:101], v[100:101], v[108:109]
	v_cvt_pk_bf16_f32 v104, v98, v99
	v_cvt_pk_bf16_f32 v105, v100, v101
	global_store_dwordx4 v[192:193], v[102:105], off
	v_lshl_add_u64 v[192:193], v[192:193], 0, s[98:99]
	v_pk_mul_f32 v[94:95], v[94:95], v[182:183] op_sel_hi:[1,0]
	v_pk_mul_f32 v[96:97], v[96:97], v[182:183] op_sel_hi:[1,0]
	v_pk_mul_f32 v[90:91], v[90:91], v[182:183] op_sel_hi:[1,0]
	v_pk_mul_f32 v[92:93], v[92:93], v[182:183] op_sel_hi:[1,0]
	v_pk_mul_f32 v[86:87], v[86:87], v[182:183] op_sel_hi:[1,0]
	v_pk_mul_f32 v[88:89], v[88:89], v[182:183] op_sel_hi:[1,0]
	v_pk_mul_f32 v[82:83], v[82:83], v[182:183] op_sel_hi:[1,0]
	v_pk_mul_f32 v[84:85], v[84:85], v[182:183] op_sel_hi:[1,0]
	v_pk_mul_f32 v[168:169], v[94:95], v[172:173] op_sel_hi:[1,0]
	v_pk_mul_f32 v[170:171], v[96:97], v[172:173] op_sel_hi:[1,0]
	v_exp_f32_e32 v168, v168
	v_exp_f32_e32 v169, v169
	v_exp_f32_e32 v170, v170
	v_exp_f32_e32 v171, v171
	v_pk_add_f32 v[168:169], v[168:169], v[174:175] op_sel_hi:[1,0]
	v_pk_add_f32 v[170:171], v[170:171], v[174:175] op_sel_hi:[1,0]
	v_rcp_f32_e32 v168, v168
	v_rcp_f32_e32 v169, v169
	v_rcp_f32_e32 v170, v170
	v_rcp_f32_e32 v171, v171
	v_pk_mul_f32 v[94:95], v[94:95], v[168:169]
	v_pk_mul_f32 v[96:97], v[96:97], v[170:171]
	v_pk_mul_f32 v[86:87], v[86:87], v[94:95]
	v_pk_mul_f32 v[88:89], v[88:89], v[96:97]
	v_cvt_pk_bf16_f32 v86, v86, v87
	v_cvt_pk_bf16_f32 v87, v88, v89
	v_pk_mul_f32 v[168:169], v[90:91], v[172:173] op_sel_hi:[1,0]
	v_pk_mul_f32 v[170:171], v[92:93], v[172:173] op_sel_hi:[1,0]
	v_exp_f32_e32 v168, v168
	v_exp_f32_e32 v169, v169
	v_exp_f32_e32 v170, v170
	v_exp_f32_e32 v171, v171
	v_pk_add_f32 v[168:169], v[168:169], v[174:175] op_sel_hi:[1,0]
	v_pk_add_f32 v[170:171], v[170:171], v[174:175] op_sel_hi:[1,0]
	v_rcp_f32_e32 v168, v168
	v_rcp_f32_e32 v169, v169
	v_rcp_f32_e32 v170, v170
	v_rcp_f32_e32 v171, v171
	v_pk_mul_f32 v[90:91], v[90:91], v[168:169]
	v_pk_mul_f32 v[92:93], v[92:93], v[170:171]
	v_pk_mul_f32 v[82:83], v[82:83], v[90:91]
	v_pk_mul_f32 v[84:85], v[84:85], v[92:93]
	v_cvt_pk_bf16_f32 v88, v82, v83
	v_cvt_pk_bf16_f32 v89, v84, v85
	global_store_dwordx4 v[192:193], v[86:89], off
	v_lshl_add_u64 v[192:193], v[192:193], 0, s[100:101]
	v_pk_mul_f32 v[78:79], v[78:79], v[184:185] op_sel_hi:[1,0]
	v_pk_mul_f32 v[80:81], v[80:81], v[184:185] op_sel_hi:[1,0]
	v_pk_mul_f32 v[74:75], v[74:75], v[184:185] op_sel_hi:[1,0]
	v_pk_mul_f32 v[76:77], v[76:77], v[184:185] op_sel_hi:[1,0]
	v_pk_mul_f32 v[70:71], v[70:71], v[184:185] op_sel_hi:[1,0]
	v_pk_mul_f32 v[72:73], v[72:73], v[184:185] op_sel_hi:[1,0]
	v_pk_mul_f32 v[66:67], v[66:67], v[184:185] op_sel_hi:[1,0]
	v_pk_mul_f32 v[68:69], v[68:69], v[184:185] op_sel_hi:[1,0]
	v_pk_mul_f32 v[168:169], v[78:79], v[172:173] op_sel_hi:[1,0]
	v_pk_mul_f32 v[170:171], v[80:81], v[172:173] op_sel_hi:[1,0]
	v_exp_f32_e32 v168, v168
	v_exp_f32_e32 v169, v169
	v_exp_f32_e32 v170, v170
	v_exp_f32_e32 v171, v171
	v_pk_add_f32 v[168:169], v[168:169], v[174:175] op_sel_hi:[1,0]
	v_pk_add_f32 v[170:171], v[170:171], v[174:175] op_sel_hi:[1,0]
	v_rcp_f32_e32 v168, v168
	v_rcp_f32_e32 v169, v169
	v_rcp_f32_e32 v170, v170
	v_rcp_f32_e32 v171, v171
	v_pk_mul_f32 v[78:79], v[78:79], v[168:169]
	v_pk_mul_f32 v[80:81], v[80:81], v[170:171]
	v_pk_mul_f32 v[70:71], v[70:71], v[78:79]
	v_pk_mul_f32 v[72:73], v[72:73], v[80:81]
	v_cvt_pk_bf16_f32 v70, v70, v71
	v_cvt_pk_bf16_f32 v71, v72, v73
	v_pk_mul_f32 v[168:169], v[74:75], v[172:173] op_sel_hi:[1,0]
	v_pk_mul_f32 v[170:171], v[76:77], v[172:173] op_sel_hi:[1,0]
	v_exp_f32_e32 v168, v168
	v_exp_f32_e32 v169, v169
	v_exp_f32_e32 v170, v170
	v_exp_f32_e32 v171, v171
	v_pk_add_f32 v[168:169], v[168:169], v[174:175] op_sel_hi:[1,0]
	v_pk_add_f32 v[170:171], v[170:171], v[174:175] op_sel_hi:[1,0]
	v_rcp_f32_e32 v168, v168
	v_rcp_f32_e32 v169, v169
	v_rcp_f32_e32 v170, v170
	v_rcp_f32_e32 v171, v171
	v_pk_mul_f32 v[74:75], v[74:75], v[168:169]
	v_pk_mul_f32 v[76:77], v[76:77], v[170:171]
	v_pk_mul_f32 v[66:67], v[66:67], v[74:75]
	v_pk_mul_f32 v[68:69], v[68:69], v[76:77]
	v_cvt_pk_bf16_f32 v72, v66, v67
	v_cvt_pk_bf16_f32 v73, v68, v69
	global_store_dwordx4 v[192:193], v[70:73], off
	v_lshl_add_u64 v[192:193], v[192:193], 0, s[98:99]
	v_pk_mul_f32 v[62:63], v[62:63], v[186:187] op_sel_hi:[1,0]
	v_pk_mul_f32 v[64:65], v[64:65], v[186:187] op_sel_hi:[1,0]
	v_pk_mul_f32 v[58:59], v[58:59], v[186:187] op_sel_hi:[1,0]
; __device__ __forceinline__ unsigned cvt_pk_bf16(float lo, float hi) { unsigned r; asm volatile("v_cvt_pk_bf16_f32 %0, %1, %2" : "=v"(r) : "v"(lo), "v"(hi)); return r; }
; __device__ __forceinline__ float silu_f(float g) { return g * __builtin_amdgcn_rcpf(1.0f + __expf(-g)); }
;     __device__ __forceinline__ void operator()(const f32x4 (&acc)[2][2][4][2], const Unit& u, int ui, int wr, int wc, int fr, int fq) const {
;         const int row0 = u.pm * BM + wr * 64 + fr, col0 = u.pn * HALF + wc * 32 + 8 * fq;
; #pragma unroll
;         for (int ai = 0; ai < 2; ++ai)
; #pragma unroll
;             for (int m = 0; m < 4; ++m) {
;                 const int row = row0 + ai * HALF + m * 16;
;                 const float s = rsb[(ui & 1) * 256 + ai * HALF + wr * 64 + m * 16 + fr];
;                 f32x4 g0 = acc[ai][0][m][0] * s, g1 = acc[ai][0][m][1] * s, u0 = acc[ai][1][m][0] * s, u1 = acc[ai][1][m][1] * s;
;                 u32x4 w;
;                 w.x = cvt_pk_bf16(silu_f(g0[0]) * u0[0], silu_f(g0[1]) * u0[1]); w.y = cvt_pk_bf16(silu_f(g0[2]) * u0[2], silu_f(g0[3]) * u0[3]);
;                 w.z = cvt_pk_bf16(silu_f(g1[0]) * u1[0], silu_f(g1[1]) * u1[1]); w.w = cvt_pk_bf16(silu_f(g1[2]) * u1[2], silu_f(g1[3]) * u1[3]);
;                 *(u32x4*)(H + (size_t)row * ldh + col0) = w;
;             }
;     }
	v_pk_mul_f32 v[60:61], v[60:61], v[186:187] op_sel_hi:[1,0]
	v_pk_mul_f32 v[54:55], v[54:55], v[186:187] op_sel_hi:[1,0]
	v_pk_mul_f32 v[56:57], v[56:57], v[186:187] op_sel_hi:[1,0]
	v_pk_mul_f32 v[50:51], v[50:51], v[186:187] op_sel_hi:[1,0]
	v_pk_mul_f32 v[52:53], v[52:53], v[186:187] op_sel_hi:[1,0]
	v_pk_mul_f32 v[168:169], v[62:63], v[172:173] op_sel_hi:[1,0]
	v_pk_mul_f32 v[170:171], v[64:65], v[172:173] op_sel_hi:[1,0]
	v_exp_f32_e32 v168, v168
	v_exp_f32_e32 v169, v169
	v_exp_f32_e32 v170, v170
	v_exp_f32_e32 v171, v171
	v_pk_add_f32 v[168:169], v[168:169], v[174:175] op_sel_hi:[1,0]
	v_pk_add_f32 v[170:171], v[170:171], v[174:175] op_sel_hi:[1,0]
	v_rcp_f32_e32 v168, v168
	v_rcp_f32_e32 v169, v169
	v_rcp_f32_e32 v170, v170
	v_rcp_f32_e32 v171, v171
	v_pk_mul_f32 v[62:63], v[62:63], v[168:169]
	v_pk_mul_f32 v[64:65], v[64:65], v[170:171]
	v_pk_mul_f32 v[54:55], v[54:55], v[62:63]
	v_pk_mul_f32 v[56:57], v[56:57], v[64:65]
	v_cvt_pk_bf16_f32 v54, v54, v55
	v_cvt_pk_bf16_f32 v55, v56, v57
	v_pk_mul_f32 v[168:169], v[58:59], v[172:173] op_sel_hi:[1,0]
	v_pk_mul_f32 v[170:171], v[60:61], v[172:173] op_sel_hi:[1,0]
	v_exp_f32_e32 v168, v168
	v_exp_f32_e32 v169, v169
	v_exp_f32_e32 v170, v170
	v_exp_f32_e32 v171, v171
	v_pk_add_f32 v[168:169], v[168:169], v[174:175] op_sel_hi:[1,0]
	v_pk_add_f32 v[170:171], v[170:171], v[174:175] op_sel_hi:[1,0]
	v_rcp_f32_e32 v168, v168
	v_rcp_f32_e32 v169, v169
	v_rcp_f32_e32 v170, v170
	v_rcp_f32_e32 v171, v171
	v_pk_mul_f32 v[58:59], v[58:59], v[168:169]
	v_pk_mul_f32 v[60:61], v[60:61], v[170:171]
	v_pk_mul_f32 v[50:51], v[50:51], v[58:59]
	v_pk_mul_f32 v[52:53], v[52:53], v[60:61]
	v_cvt_pk_bf16_f32 v56, v50, v51
	v_cvt_pk_bf16_f32 v57, v52, v53
	global_store_dwordx4 v[192:193], v[54:57], off
	v_lshl_add_u64 v[192:193], v[192:193], 0, s[98:99]
	v_pk_mul_f32 v[46:47], v[46:47], v[188:189] op_sel_hi:[1,0]
	v_pk_mul_f32 v[48:49], v[48:49], v[188:189] op_sel_hi:[1,0]
	v_pk_mul_f32 v[42:43], v[42:43], v[188:189] op_sel_hi:[1,0]
	v_pk_mul_f32 v[44:45], v[44:45], v[188:189] op_sel_hi:[1,0]
	v_pk_mul_f32 v[38:39], v[38:39], v[188:189] op_sel_hi:[1,0]
	v_pk_mul_f32 v[40:41], v[40:41], v[188:189] op_sel_hi:[1,0]
	v_pk_mul_f32 v[34:35], v[34:35], v[188:189] op_sel_hi:[1,0]
	v_pk_mul_f32 v[36:37], v[36:37], v[188:189] op_sel_hi:[1,0]
	v_pk_mul_f32 v[168:169], v[46:47], v[172:173] op_sel_hi:[1,0]
	v_pk_mul_f32 v[170:171], v[48:49], v[172:173] op_sel_hi:[1,0]
	v_exp_f32_e32 v168, v168
	v_exp_f32_e32 v169, v169
	v_exp_f32_e32 v170, v170
	v_exp_f32_e32 v171, v171
	v_pk_add_f32 v[168:169], v[168:169], v[174:175] op_sel_hi:[1,0]
	v_pk_add_f32 v[170:171], v[170:171], v[174:175] op_sel_hi:[1,0]
	v_rcp_f32_e32 v168, v168
	v_rcp_f32_e32 v169, v169
	v_rcp_f32_e32 v170, v170
	v_rcp_f32_e32 v171, v171
	v_pk_mul_f32 v[46:47], v[46:47], v[168:169]
	v_pk_mul_f32 v[48:49], v[48:49], v[170:171]
	v_pk_mul_f32 v[38:39], v[38:39], v[46:47]
	v_pk_mul_f32 v[40:41], v[40:41], v[48:49]
	v_cvt_pk_bf16_f32 v38, v38, v39
	v_cvt_pk_bf16_f32 v39, v40, v41
	v_pk_mul_f32 v[168:169], v[42:43], v[172:173] op_sel_hi:[1,0]
	v_pk_mul_f32 v[170:171], v[44:45], v[172:173] op_sel_hi:[1,0]
	v_exp_f32_e32 v168, v168
	v_exp_f32_e32 v169, v169
	v_exp_f32_e32 v170, v170
	v_exp_f32_e32 v171, v171
	v_pk_add_f32 v[168:169], v[168:169], v[174:175] op_sel_hi:[1,0]
	v_pk_add_f32 v[170:171], v[170:171], v[174:175] op_sel_hi:[1,0]
	v_rcp_f32_e32 v168, v168
	v_rcp_f32_e32 v169, v169
	v_rcp_f32_e32 v170, v170
	v_rcp_f32_e32 v171, v171
	v_pk_mul_f32 v[42:43], v[42:43], v[168:169]
	v_pk_mul_f32 v[44:45], v[44:45], v[170:171]
	v_pk_mul_f32 v[34:35], v[34:35], v[42:43]
	v_pk_mul_f32 v[36:37], v[36:37], v[44:45]
	v_cvt_pk_bf16_f32 v40, v34, v35
	v_cvt_pk_bf16_f32 v41, v36, v37
	global_store_dwordx4 v[192:193], v[38:41], off
	v_lshl_add_u64 v[192:193], v[192:193], 0, s[98:99]
	v_pk_mul_f32 v[30:31], v[30:31], v[190:191] op_sel_hi:[1,0]
	v_pk_mul_f32 v[32:33], v[32:33], v[190:191] op_sel_hi:[1,0]
	v_pk_mul_f32 v[26:27], v[26:27], v[190:191] op_sel_hi:[1,0]
	v_pk_mul_f32 v[28:29], v[28:29], v[190:191] op_sel_hi:[1,0]
	v_pk_mul_f32 v[22:23], v[22:23], v[190:191] op_sel_hi:[1,0]
	v_pk_mul_f32 v[24:25], v[24:25], v[190:191] op_sel_hi:[1,0]
	v_pk_mul_f32 v[18:19], v[18:19], v[190:191] op_sel_hi:[1,0]
	v_pk_mul_f32 v[20:21], v[20:21], v[190:191] op_sel_hi:[1,0]
	v_pk_mul_f32 v[168:169], v[30:31], v[172:173] op_sel_hi:[1,0]
	v_pk_mul_f32 v[170:171], v[32:33], v[172:173] op_sel_hi:[1,0]
	v_exp_f32_e32 v168, v168
	v_exp_f32_e32 v169, v169
	v_exp_f32_e32 v170, v170
	v_exp_f32_e32 v171, v171
	v_pk_add_f32 v[168:169], v[168:169], v[174:175] op_sel_hi:[1,0]
	v_pk_add_f32 v[170:171], v[170:171], v[174:175] op_sel_hi:[1,0]
	v_rcp_f32_e32 v168, v168
	v_rcp_f32_e32 v169, v169
	v_rcp_f32_e32 v170, v170
	v_rcp_f32_e32 v171, v171
	v_pk_mul_f32 v[30:31], v[30:31], v[168:169]
	v_pk_mul_f32 v[32:33], v[32:33], v[170:171]
	v_pk_mul_f32 v[22:23], v[22:23], v[30:31]
	v_pk_mul_f32 v[24:25], v[24:25], v[32:33]
	v_cvt_pk_bf16_f32 v22, v22, v23
	v_cvt_pk_bf16_f32 v23, v24, v25
	v_pk_mul_f32 v[168:169], v[26:27], v[172:173] op_sel_hi:[1,0]
	v_pk_mul_f32 v[170:171], v[28:29], v[172:173] op_sel_hi:[1,0]
	v_exp_f32_e32 v168, v168
	v_exp_f32_e32 v169, v169
	v_exp_f32_e32 v170, v170
	v_exp_f32_e32 v171, v171
	v_pk_add_f32 v[168:169], v[168:169], v[174:175] op_sel_hi:[1,0]
	v_pk_add_f32 v[170:171], v[170:171], v[174:175] op_sel_hi:[1,0]
	v_rcp_f32_e32 v168, v168
	v_rcp_f32_e32 v169, v169
	v_rcp_f32_e32 v170, v170
	v_rcp_f32_e32 v171, v171
	v_pk_mul_f32 v[26:27], v[26:27], v[168:169]
	v_pk_mul_f32 v[28:29], v[28:29], v[170:171]
	v_pk_mul_f32 v[18:19], v[18:19], v[26:27]
	v_pk_mul_f32 v[20:21], v[20:21], v[28:29]
	v_cvt_pk_bf16_f32 v24, v18, v19
	v_cvt_pk_bf16_f32 v25, v20, v21
	s_mov_b64 s[2:3], -1
	s_cmp_eq_u32 s61, 10
	global_store_dwordx4 v[192:193], v[22:25], off
	s_cbranch_scc1 .LBB0_117
;     static __device__ __forceinline__ float fin(const f32x4& a, const f32x4& b, const f32x4& c, const f32x4& d) {
;         const float s = (((a[0] + a[1]) + (a[2] + a[3])) + ((b[0] + b[1]) + (b[2] + b[3]))) + (((c[0] + c[1]) + (c[2] + c[3])) + ((d[0] + d[1]) + (d[2] + d[3])));
;         return 1.0f / sqrtf(s * (1.0f / 1024.0f) + 1e-6f); }
;     __device__ __forceinline__ void issue(const Unit& u, Pre& p) const {
;         int t = threadIdx.x; asm volatile("" : "+v"(t));
;         if (t < 256) { gp_t g = (gp_t)(ssq + (size_t)(u.pm * BM + t) * 16); p.a = g[0]; p.b = g[1]; p.c = g[2]; p.d = g[3]; }
;     }
;     __device__ __forceinline__ void commit(const Unit& u, int ui, const Pre& p) const {
;         int t = threadIdx.x; asm volatile("" : "+v"(t));
;         if (t < 256) rsb[(ui & 1) * 256 + t] = fin(p.a, p.b, p.c, p.d);
;     }
	s_nop 0
	v_add_u32_e32 v18, 0xffffff00, v204
	s_nop 0
	v_cmp_gt_u32_e32 vcc, s68, v18
	s_and_saveexec_b64 s[20:21], vcc
	s_cbranch_execz .LBB0_131
	s_waitcnt vmcnt(8)
	v_mov_b32_e32 v20, v6
	v_mov_b32_e32 v21, v14
	v_mov_b32_e32 v22, v7
	v_mov_b32_e32 v23, v15
	v_pk_add_f32 v[20:21], v[20:21], v[22:23]
	v_mov_b32_e32 v22, v8
	v_mov_b32_e32 v23, v16
	v_mov_b32_e32 v24, v9
	v_mov_b32_e32 v25, v17
	v_pk_add_f32 v[22:23], v[22:23], v[24:25]
	v_mov_b32_e32 v24, v3
	v_pk_add_f32 v[20:21], v[20:21], v[22:23]
	v_mov_b32_e32 v22, v2
	v_mov_b32_e32 v23, v10
	v_mov_b32_e32 v25, v11
	v_pk_add_f32 v[22:23], v[22:23], v[24:25]
	v_mov_b32_e32 v24, v4
	v_mov_b32_e32 v25, v12
	v_mov_b32_e32 v26, v5
	v_mov_b32_e32 v27, v13
	v_pk_add_f32 v[24:25], v[24:25], v[26:27]
	s_nop 0
	v_pk_add_f32 v[22:23], v[22:23], v[24:25]
	s_nop 0
	v_pk_add_f32 v[20:21], v[22:23], v[20:21]
	s_nop 0
	v_add_f32_e32 v19, v20, v21
	v_fmamk_f32 v19, v19, 0x3a800000, v205
	v_mul_f32_e32 v20, 0x4f800000, v19
	v_cmp_gt_f32_e32 vcc, s69, v19
	s_nop 1
	v_cndmask_b32_e32 v19, v19, v20, vcc
	v_sqrt_f32_e32 v20, v19
	s_nop 0
	v_add_u32_e32 v21, -1, v20
	v_fma_f32 v22, -v21, v20, v19
	v_cmp_ge_f32_e64 s[2:3], 0, v22
	v_add_u32_e32 v22, 1, v20
	s_nop 0
	v_cndmask_b32_e64 v21, v20, v21, s[2:3]
	v_fma_f32 v20, -v22, v20, v19
	v_cmp_lt_f32_e64 s[2:3], 0, v20
	s_nop 1
	v_cndmask_b32_e64 v20, v21, v22, s[2:3]
	v_mul_f32_e32 v21, 0x37800000, v20
	v_cndmask_b32_e32 v20, v20, v21, vcc
	v_cmp_class_f32_e32 vcc, v19, v206
	s_nop 1
	v_cndmask_b32_e32 v19, v20, v19, vcc
	v_div_scale_f32 v20, s[2:3], v19, v19, 1.0
	v_rcp_f32_e32 v21, v20
	s_lshl_b32 s2, s60, 10
	s_and_b32 s2, s2, 0x400
	s_add_i32 s2, s2, 0
	v_fma_f32 v22, -v20, v21, 1.0
	v_fmac_f32_e32 v21, v22, v21
	v_div_scale_f32 v22, vcc, 1.0, v19, 1.0
	v_mul_f32_e32 v23, v22, v21
	v_fma_f32 v24, -v20, v23, v22
	v_fmac_f32_e32 v23, v24, v21
	v_fma_f32 v20, -v20, v23, v22
	v_div_fmas_f32 v20, v20, v21, v23
	v_lshl_add_u32 v18, v18, 2, s2
	v_div_fixup_f32 v19, v20, v19, 1.0
	v_add_u32_e32 v18, 0x20400, v18
	ds_write_b32 v18, v19

;     __device__ __forceinline__ void issue(const Unit& u, Pre& p) const {
;         int t = threadIdx.x; asm volatile("" : "+v"(t));
;         if (t < 256) { gp_t g = (gp_t)(ssq + (size_t)(u.pm * BM + t) * 16); p.a = g[0]; p.b = g[1]; p.c = g[2]; p.d = g[3]; }
;     }
.LBB0_322:
	s_andn2_b64 vcc, exec, s[2:3]
	s_cbranch_vccnz .LBB0_326
	v_add_u32_e32 v146, 0xffffff00, v204
	s_nop 0
	v_cmp_gt_u32_e32 vcc, s68, v146
	s_and_saveexec_b64 s[2:3], vcc
	s_cbranch_execz .LBB0_325
	s_nop 0
	v_lshl_add_u32 v2, s16, 8, v146
	v_ashrrev_i32_e32 v3, 31, v2
	v_lshlrev_b64 v[2:3], 6, v[2:3]
	v_lshl_add_u64 v[14:15], s[4:5], 0, v[2:3]
	global_load_dwordx4 v[2:5], v[14:15], off offset:48
	global_load_dwordx4 v[6:9], v[14:15], off offset:32
	global_load_dwordx4 v[10:13], v[14:15], off offset:16
	s_nop 0
	global_load_dwordx4 v[14:17], v[14:15], off

;     static __device__ __forceinline__ float fin(const f32x4& a, const f32x4& b, const f32x4& c, const f32x4& d) {
;         const float s = (((a[0] + a[1]) + (a[2] + a[3])) + ((b[0] + b[1]) + (b[2] + b[3]))) + (((c[0] + c[1]) + (c[2] + c[3])) + ((d[0] + d[1]) + (d[2] + d[3])));
;         return 1.0f / sqrtf(s * (1.0f / 1024.0f) + 1e-6f); }
;     __device__ __forceinline__ void issue(const Unit& u, Pre& p) const {
;         int t = threadIdx.x; asm volatile("" : "+v"(t));
;         if (t < 256) { gp_t g = (gp_t)(ssq + (size_t)(u.pm * BM + t) * 16); p.a = g[0]; p.b = g[1]; p.c = g[2]; p.d = g[3]; }
;     }
;     __device__ __forceinline__ void commit(const Unit& u, int ui, const Pre& p) const {
;         int t = threadIdx.x; asm volatile("" : "+v"(t));
;         if (t < 256) rsb[(ui & 1) * 256 + t] = fin(p.a, p.b, p.c, p.d);
;     }
.LBB0_331:
	v_add_u32_e32 v18, 0xffffff00, v204
	s_nop 0
	v_cmp_gt_u32_e32 vcc, s68, v18
	s_and_saveexec_b64 s[24:25], vcc
	s_cbranch_execz .LBB0_333
	s_waitcnt vmcnt(16)
	v_mov_b32_e32 v20, v6
	v_mov_b32_e32 v21, v14
	v_mov_b32_e32 v22, v7
	v_mov_b32_e32 v23, v15
	v_pk_add_f32 v[20:21], v[20:21], v[22:23]
	v_mov_b32_e32 v22, v8
	v_mov_b32_e32 v23, v16
	v_mov_b32_e32 v24, v9
	v_mov_b32_e32 v25, v17
	v_pk_add_f32 v[22:23], v[22:23], v[24:25]
	v_mov_b32_e32 v24, v3
	v_pk_add_f32 v[20:21], v[20:21], v[22:23]
	v_mov_b32_e32 v22, v2
	v_mov_b32_e32 v23, v10
	v_mov_b32_e32 v25, v11
	v_pk_add_f32 v[22:23], v[22:23], v[24:25]
	v_mov_b32_e32 v24, v4
	v_mov_b32_e32 v25, v12
	v_mov_b32_e32 v26, v5
	v_mov_b32_e32 v27, v13
	v_pk_add_f32 v[24:25], v[24:25], v[26:27]
	s_nop 0
	v_pk_add_f32 v[22:23], v[22:23], v[24:25]
	s_nop 0
	v_pk_add_f32 v[20:21], v[22:23], v[20:21]
	s_nop 0
	v_add_f32_e32 v19, v20, v21
	v_fmamk_f32 v19, v19, 0x3a800000, v205
	v_mul_f32_e32 v20, 0x4f800000, v19
	v_cmp_gt_f32_e32 vcc, s69, v19
	s_nop 1
	v_cndmask_b32_e32 v19, v19, v20, vcc
	v_sqrt_f32_e32 v20, v19
	s_nop 0
	v_add_u32_e32 v21, -1, v20
	v_fma_f32 v22, -v21, v20, v19
	v_cmp_ge_f32_e64 s[2:3], 0, v22
	v_add_u32_e32 v22, 1, v20
	s_nop 0
	v_cndmask_b32_e64 v21, v20, v21, s[2:3]
	v_fma_f32 v20, -v22, v20, v19
	v_cmp_lt_f32_e64 s[2:3], 0, v20
	s_nop 1
	v_cndmask_b32_e64 v20, v21, v22, s[2:3]
	v_mul_f32_e32 v21, 0x37800000, v20
	v_cndmask_b32_e32 v20, v20, v21, vcc
	v_cmp_class_f32_e32 vcc, v19, v206
	s_nop 1
	v_cndmask_b32_e32 v19, v20, v19, vcc
	v_div_scale_f32 v20, s[2:3], v19, v19, 1.0
	v_rcp_f32_e32 v21, v20
	s_lshl_b32 s2, s65, 10
	s_and_b32 s2, s2, 0x400
	s_add_i32 s2, s2, 0
	v_fma_f32 v22, -v20, v21, 1.0
	v_fmac_f32_e32 v21, v22, v21
	v_div_scale_f32 v22, vcc, 1.0, v19, 1.0
	v_mul_f32_e32 v23, v22, v21
	v_fma_f32 v24, -v20, v23, v22
	v_fmac_f32_e32 v23, v24, v21
	v_fma_f32 v20, -v20, v23, v22
	v_div_fmas_f32 v20, v20, v21, v23
	v_lshl_add_u32 v18, v18, 2, s2
	v_div_fixup_f32 v19, v20, v19, 1.0
	v_add_u32_e32 v18, 0x20400, v18
	ds_write_b32 v18, v19
